# base15 + K prologue: 4 gathered-row index loads issued together and B-operand DMA before the wait
# baseline (speedup 1.0000x reference)
;     int tid_ = threadIdx.x; asm volatile("" : "+v"(tid_));
;     const int tid = tid_, wid = __builtin_amdgcn_readfirstlane(tid >> 6), lane = tid & 63, wr = wid >> 2, wc = wid & 3, fr = lane & 15, fq = lane >> 4;
;     constexpr bool FP8 = (ESZ == 1);
;     const int K = g.K, nt = K * ESZ / (BK * 2);
;     unsigned voffA[2], voffB[2]; int gR[2]; unsigned gC2[2];
; #pragma unroll
;     for (int i = 0; i < 2; ++i) { int R, C; stage_rc(tid * 16 + i * 8192, R, C); const int Rb = Epi::PERM ? ((R & ~31) + perm32(R & 31)) : R;
;         voffA[i] = (unsigned)(R * g.lda * ESZ + C * 2); voffB[i] = (unsigned)(Rb * g.ldb * ESZ + C * 2); gR[i] = R; gC2[i] = (unsigned)C * 2u; }
;     unsigned gc0[2] = {voffA[0], voffA[1]}, gc1[2] = {voffA[0], voffA[1]};
;     int gn0r[2] = {0, 0}, gn1r[2] = {0, 0};
;     const size_t kstep = (size_t)(BK * 2);
;     const size_t hstepA = GATHER ? (size_t)0 : (size_t)HALF * g.lda * ESZ, hstepB = (size_t)HALF * g.ldb * ESZ;
;     const unsigned ldsw = (unsigned)wid * 1024u;
;     const int aoff = lds_byte(wr * 64 + fr, FP8 ? fq * 16 : fq * 8), boff = lds_byte(wc * 32 + fr, FP8 ? fq * 16 : fq * 8);
;     const int sel8 = FP8 ? ((fq & 1) << 4) : 0; const int aoff1 = aoff + sel8, aoff2 = aoff + 16 - sel8, boff1 = boff + sel8, boff2 = boff + 16 - sel8;
;     ...
;     Unit cur, nxt; int ui = 0;
;     if (!S.next(0, cur)) return;
;     f32x4 acc[2][2][4][2];
; #pragma unroll
;     for (int a = 0; a < 2; ++a)
; #pragma unroll
;         for (int b = 0; b < 2; ++b)
; #pragma unroll
;             for (int m = 0; m < 4; ++m)
; #pragma unroll
;                 for (int n = 0; n < 2; ++n) acc[a][b][m][n] = (f32x4){0.f, 0.f, 0.f, 0.f};
;     bf16x8 At[4][2], B0[2][2], B1[2][2];
;     v8i At8[4], B08[2], B18[2];
;     const int vsw = g.sw, vsx = g.sx;
;     const char* cA = cur.A; const char* cB = cur.B;
;     S.a_ready(cur);
;     if constexpr (GATHER) {
; #pragma unroll
;         for (int i = 0; i < 2; ++i) { gc0[i] = (unsigned)selrow[cur.pm * 256 + gR[i]] * (unsigned)(g.lda * ESZ) + gC2[i]; gc1[i] = (unsigned)selrow[cur.pm * 256 + 128 + gR[i]] * (unsigned)(g.lda * ESZ) + gC2[i]; } }
;     if constexpr (SP2) {
;         PG8_STAGE(PG8_SB(0, 0), cB, voffB); PG8_STAGE(PG8_SB(0, 1), cB + hstepB, voffB); PG8_STAGE(PG8_SA(0, 0), cA, gc0); PG8_STAGE(PG8_SA(0, 1), cA + hstepA, gc1);
.LBB0_2390:
	s_andn2_b64 vcc, exec, s[0:1]
	s_cbranch_vccnz .LBB0_2466
	v_readlane_b32 s0, v254, 60
	v_readlane_b32 s2, v254, 32
	v_mov_b32_e32 v2, v0
	v_readlane_b32 s16, v252, 0
	v_readlane_b32 s1, v254, 61
	v_readlane_b32 s3, v254, 33
	s_lshl_b32 s2, s24, 3
	s_load_dword s17, s[0:1], 0x0
	s_mov_b64 s[0:1], s[52:53]
	v_mov_b32_e32 v6, v0
	v_writelane_b32 v254, s2, 32
	s_waitcnt lgkmcnt(0)
	s_cmp_ge_i32 s16, s2
	v_readfirstlane_b32 s12, v6
	v_writelane_b32 v254, s3, 33
	s_cbranch_scc1 .LBB0_2412
	s_waitcnt vmcnt(0)
	v_bfe_i32 v4, v6, 27, 1
	v_lshlrev_b32_e32 v2, 4, v6
	v_lshrrev_b32_e32 v4, 22, v4
	v_add_u32_e32 v4, v2, v4
	v_and_b32_e32 v4, 0xfffffc00, v4
	v_sub_u32_e32 v4, v2, v4
	v_ashrrev_i32_e32 v3, 31, v6
	v_lshrrev_b32_e32 v5, 4, v4
	v_lshrrev_b32_e32 v3, 26, v3
	v_bitop3_b32 v4, v5, v4, 32 bitop3:0x6c
	v_add_u32_e32 v3, v6, v3
	v_ashrrev_i32_e32 v7, 31, v4
	v_ashrrev_i32_e32 v3, 6, v3
	v_lshrrev_b32_e32 v7, 26, v7
	v_lshlrev_b32_e32 v5, 3, v3
	v_add_u32_e32 v7, v4, v7
	v_and_b32_e32 v5, -16, v5
	v_ashrrev_i32_e32 v8, 6, v7
	v_add_u32_e32 v188, v8, v5
	v_and_b32_e32 v5, 0xc0, v7
	v_sub_u32_e32 v4, v4, v5
	v_lshlrev_b32_e32 v3, 5, v3
	v_ashrrev_i16_sdwa v4, v1, sext(v4) dst_sel:DWORD dst_unused:UNUSED_PAD src0_sel:DWORD src1_sel:BYTE_0
	v_and_b32_e32 v3, 32, v3
	v_bfe_i32 v4, v4, 0, 16
	v_add_u32_e32 v2, 0x2000, v2
	v_add_lshl_u32 v189, v3, v4, 1
	v_ashrrev_i32_e32 v3, 31, v2
	v_lshrrev_b32_e32 v3, 22, v3
	v_add_u32_e32 v3, v2, v3
	v_ashrrev_i32_e32 v3, 10, v3
	v_mul_i32_i24_e32 v4, 0x400, v3
	v_sub_u32_e32 v2, v2, v4
	v_lshrrev_b32_e32 v4, 4, v2
	v_bitop3_b32 v2, v4, v2, 32 bitop3:0x6c
	v_ashrrev_i32_e32 v5, 31, v2
	v_lshrrev_b32_e32 v5, 26, v5
	v_lshlrev_b32_e32 v4, 3, v3
	v_add_u32_e32 v5, v2, v5
	v_and_b32_e32 v4, -16, v4
	v_ashrrev_i32_e32 v7, 6, v5
	v_add_u32_e32 v190, v7, v4
	v_and_b32_e32 v4, 0xc0, v5
	v_sub_u32_e32 v2, v2, v4
	s_add_u32 s4, s0, 0x12300000
	v_lshlrev_b32_e32 v3, 5, v3
	v_ashrrev_i16_sdwa v2, v1, sext(v2) dst_sel:DWORD dst_unused:UNUSED_PAD src0_sel:DWORD src1_sel:BYTE_0
	s_addc_u32 s5, s1, 0
	v_and_b32_e32 v3, 32, v3
	v_bfe_i32 v2, v2, 0, 16
	s_add_u32 s25, s0, 0x3300000
	v_add_lshl_u32 v191, v3, v2, 1
	v_and_b32_e32 v2, 3, v7
	s_mov_b32 s2, 0x3fffe0
	v_lshrrev_b32_e32 v3, 2, v190
	v_lshlrev_b32_e32 v4, 1, v190
	s_addc_u32 s26, s1, 0
	v_and_or_b32 v2, v190, s2, v2
	v_and_b32_e32 v3, 4, v3
	v_and_b32_e32 v4, 24, v4
	s_add_u32 s6, s0, 0x1c80000
	v_or3_b32 v2, v2, v3, v4
	s_addc_u32 s7, s1, 0
	v_lshl_add_u32 v164, v2, 10, v191
	v_and_b32_e32 v2, 3, v8
	s_ashr_i32 s28, s16, 31
	v_and_or_b32 v2, v188, s2, v2
	s_lshr_b32 s2, s28, 29
	s_add_i32 s2, s16, s2
	s_ashr_i32 s14, s12, 6
	s_ashr_i32 s3, s2, 3
	s_and_b32 s2, s2, -8
	s_ashr_i32 s13, s12, 8
	s_lshl_b32 s27, s14, 10
	s_sub_i32 s2, s16, s2
	s_or_b32 s29, s24, 1
	s_cmp_lt_i32 s2, 0
	s_cselect_b32 s8, s29, s24
	s_mul_i32 s2, s2, s8
	s_add_i32 s2, s2, s3
	s_ashr_i32 s3, s2, 31
	s_lshr_b32 s3, s3, 26
	s_add_i32 s3, s2, s3
	s_ashr_i32 s8, s3, 6
	s_lshl_b32 s8, s8, 3
	s_sub_i32 s9, s24, s8
	v_lshrrev_b32_e32 v3, 2, v188
	v_lshlrev_b32_e32 v4, 1, v188
	s_min_i32 s9, s9, 8
	s_andn2_b32 s3, s3, 63
	v_and_b32_e32 v3, 4, v3
	v_and_b32_e32 v4, 24, v4
	s_sub_i32 s11, s2, s3
	s_sext_i32_i8 s2, s9
	v_or3_b32 v2, v2, v3, v4
	v_cvt_f32_i32_e32 v3, s2
	v_lshl_add_u32 v166, v2, 10, v189
	v_cvt_f32_i32_e32 v2, s11
	s_xor_b32 s3, s11, s2
	v_rcp_iflag_f32_e32 v4, v3
	s_ashr_i32 s3, s3, 30
	s_or_b32 s10, s3, 1
	v_mov_b32_e32 v167, v51
	v_mul_f32_e32 v4, v2, v4
	v_trunc_f32_e32 v4, v4
	v_fma_f32 v2, -v4, v3, v2
	v_cvt_i32_f32_e32 v4, v4
	v_cmp_ge_f32_e64 s[2:3], |v2|, |v3|
	s_and_b64 s[2:3], s[2:3], exec
	s_cselect_b32 s2, s10, 0
	v_readfirstlane_b32 s3, v4
	s_add_i32 s10, s3, s2
	s_mul_i32 s2, s10, s9
	s_sub_i32 s2, s11, s2
	s_sext_i32_i8 s2, s2
	s_add_i32 s23, s8, s2
	s_add_i32 s3, s23, 0xffffff00
	s_ashr_i32 s2, s23, 4
	s_lshr_b32 s3, s3, 1
	s_cmpk_lt_i32 s23, 0x100
	s_cselect_b32 s2, s2, s3
	s_ashr_i32 s3, s2, 31
	s_lshl_b64 s[2:3], s[2:3], 21
	s_add_u32 s8, s25, s2
	s_addc_u32 s9, s26, s3
	s_bfe_i64 s[2:3], s[10:11], 0x80000
	s_lshl_b64 s[2:3], s[2:3], 18
	s_add_u32 s2, s8, s2
	s_addc_u32 s3, s9, s3
	s_lshl_b32 s8, s23, 8
	v_add_u32_e32 v2, s8, v188
	v_ashrrev_i32_e32 v3, 31, v2
	v_lshl_add_u64 v[2:3], v[2:3], 2, s[6:7]
	global_load_dword v168, v[2:3], off
	s_or_b32 s9, s8, 0x80
	v_add_u32_e32 v2, s9, v188
	v_ashrrev_i32_e32 v3, 31, v2
	v_lshl_add_u64 v[2:3], v[2:3], 2, s[6:7]
	global_load_dword v170, v[2:3], off
	v_add_u32_e32 v2, s8, v190
	v_ashrrev_i32_e32 v3, 31, v2
	v_lshl_add_u64 v[2:3], v[2:3], 2, s[6:7]
	global_load_dword v172, v[2:3], off
	v_add_u32_e32 v2, s9, v190
	v_ashrrev_i32_e32 v3, 31, v2
	v_lshl_add_u64 v[2:3], v[2:3], 2, s[6:7]
	global_load_dword v174, v[2:3], off
	s_add_i32 s30, s27, 0
	s_add_i32 m0, s30, 0x10000
	v_mov_b32_e32 v165, v51
	v_lshl_add_u64 v[4:5], s[2:3], 0, v[164:165]
	global_load_lds_dwordx4 v166, s[2:3]
	s_add_i32 m0, s30, 0x12000
	s_add_u32 s8, s2, 0x20000
	global_load_lds_dwordx4 v164, s[2:3]
	s_addc_u32 s9, s3, 0
	s_add_i32 m0, s30, 0x14000
	s_add_i32 s31, s30, 0x2000
	global_load_lds_dwordx4 v166, s[8:9]
	s_add_i32 m0, s30, 0x16000
	s_add_i32 s34, s30, 0x4000
	global_load_lds_dwordx4 v164, s[8:9]
	s_waitcnt vmcnt(4)
	v_lshl_add_u32 v168, v168, 10, v189
	v_lshl_add_u32 v170, v170, 10, v189
	v_lshl_add_u32 v172, v172, 10, v191
	v_lshl_add_u32 v174, v174, 10, v191
	s_mov_b32 m0, s30
	s_add_i32 s35, s30, 0x6000
	global_load_lds_dwordx4 v168, s[4:5]
	s_mov_b32 m0, s31
	s_cmp_eq_u32 s13, 1
	global_load_lds_dwordx4 v172, s[4:5]
	s_mov_b32 m0, s34
	v_lshl_add_u64 v[2:3], s[2:3], 0, v[166:167]
	global_load_lds_dwordx4 v170, s[4:5]
	s_mov_b32 m0, s35
	s_cselect_b64 s[8:9], -1, 0
	global_load_lds_dwordx4 v174, s[4:5]
	s_cmp_lg_u32 s13, 1
	s_cbranch_scc1 .LBB0_2394
	s_barrier
